# GDN prep: hand-written 16x16 diagonal-block inverse (36 b128 row reads through a 10-quad ring, two-row interleaved fma)
# speedup vs baseline: 1.0127x; 1.0127x over previous
; DI f32x4 mfma16(bf16x8 a, bf16x8 b, f32x4 c) { return __builtin_amdgcn_mfma_f32_16x16x32_bf16(a, b, c, 0, 0, 0); }
; DI void gdn_prep_item(const P& p, int l, int item, unsigned char* smem) {
;     ...
;         const int mt = w >> 1;
; #pragma unroll
;         for (int n2 = 0; n2 < 2; ++n2) {
;             const int nt = 2 * (w & 1) + n2;
;             f32x4 aL = (f32x4){0.f, 0.f, 0.f, 0.f}, aA = (f32x4){0.f, 0.f, 0.f, 0.f};
; #pragma unroll
;             for (int ks = 0; ks < 4; ++ks) {
;                 const bf16x8 bk = ld8(sK + (16 * nt + l15) * 136 + 32 * ks + 8 * g);
;                 aL = mfma16(bk, ld8(sKB + (16 * mt + l15) * 136 + 32 * ks + 8 * g), aL);
;                 aA = mfma16(bk, ld8(sQ + (16 * mt + l15) * 136 + 32 * ks + 8 * g), aA);
;             }
;             const int ii = 16 * mt + l15, j0 = 16 * nt + 4 * g;
;             const f32x4 cj = *(const f32x4*)(scum + j0); const float ci = scum[ii];
;             f32x4 lv; float av[4];
; #pragma unroll
;             for (int r = 0; r < 4; ++r) {
;                 const float dcy = __expf(fminf(ci - cj[r], 0.f));
;                 lv[r] = (j0 + r < ii) ? aL[r] * dcy : 0.f;
;                 av[r] = (j0 + r <= ii) ? aA[r] * dcy : 0.f;
;             }
;             *(f32x4*)(sL + ii * LS + j0) = lv;
;             { u32x2 lb; lb.x = pk2(lv[0], lv[1]); lb.y = pk2(lv[2], lv[3]); *(u32x2*)(sLb + ii * 72 + j0) = lb; }
;             { u32x2 ab; ab.x = pk2(av[0], av[1]); ab.y = pk2(av[2], av[3]); *(u32x2*)(AT + (((size_t)seq * 36 + c) * 64 + ii) * 64 + j0) = ab; }
;         }
;     }
;     __syncthreads();
.LBB0_328:
	s_or_b64 exec, exec, s[82:83]
	s_waitcnt lgkmcnt(0)
	s_barrier
	ds_read_b128 v[16:19], v197
	ds_read_b128 v[20:23], v107 offset:17408
	ds_read_b128 v[24:27], v107 offset:34816
	s_waitcnt lgkmcnt(1)
	v_mfma_f32_16x16x32_bf16 v[20:23], v[16:19], v[20:23], 0
	s_ashr_i32 s6, vcc_hi, 31
	s_mul_hi_i32 s5, vcc_lo, 36
	s_add_u32 s4, s20, vcc_hi
	s_waitcnt lgkmcnt(0)
	v_mfma_f32_16x16x32_bf16 v[16:19], v[16:19], v[24:27], 0
	ds_read_b128 v[24:27], v197 offset:64
	ds_read_b128 v[28:31], v107 offset:17472
	s_addc_u32 s5, s5, s6
	s_lshl_b64 s[4:5], s[4:5], 13
	s_waitcnt lgkmcnt(0)
	v_mfma_f32_16x16x32_bf16 v[20:23], v[24:27], v[28:31], v[20:23]
	ds_read_b128 v[28:31], v107 offset:34880
	v_lshl_add_u64 v[122:123], v[84:85], 0, s[4:5]
	s_waitcnt lgkmcnt(0)
	v_mfma_f32_16x16x32_bf16 v[16:19], v[24:27], v[28:31], v[16:19]
	ds_read_b128 v[24:27], v197 offset:128
	ds_read_b128 v[28:31], v107 offset:17536
	s_waitcnt lgkmcnt(0)
	v_mfma_f32_16x16x32_bf16 v[20:23], v[24:27], v[28:31], v[20:23]
	ds_read_b128 v[28:31], v107 offset:34944
	s_waitcnt lgkmcnt(0)
	v_mfma_f32_16x16x32_bf16 v[16:19], v[24:27], v[28:31], v[16:19]
	ds_read_b128 v[24:27], v197 offset:192
	ds_read_b128 v[28:31], v107 offset:17600
	s_waitcnt lgkmcnt(0)
	v_mfma_f32_16x16x32_bf16 v[20:23], v[24:27], v[28:31], v[20:23]
	ds_read_b128 v[28:31], v107 offset:35008
	s_waitcnt lgkmcnt(0)
	v_mfma_f32_16x16x32_bf16 v[16:19], v[24:27], v[28:31], v[16:19]
	ds_read_b128 v[24:27], v143
	ds_read_b32 v28, v109
	s_waitcnt lgkmcnt(0)
	v_sub_f32_e32 v24, v28, v24
	v_min_f32_e32 v24, 0, v24
	v_mul_f32_e32 v24, 0x3fb8aa3b, v24
	v_exp_f32_e32 v24, v24
	s_nop 0
	v_mul_f32_e32 v29, v16, v24
	v_sub_f32_e32 v16, v28, v25
	v_min_f32_e32 v16, 0, v16
	v_mul_f32_e32 v16, 0x3fb8aa3b, v16
	v_exp_f32_e32 v16, v16
	v_mul_f32_e32 v20, v20, v24
	v_mov_b32_e32 v24, v21
	v_mov_b32_e32 v25, v22
	v_mul_f32_e32 v30, v17, v16
	v_sub_f32_e32 v17, v28, v26
	v_min_f32_e32 v17, 0, v17
	v_mul_f32_e32 v17, 0x3fb8aa3b, v17
	v_exp_f32_e32 v17, v17
	v_cndmask_b32_e64 v20, 0, v20, s[54:55]
	v_pk_mul_f32 v[24:25], v[24:25], v[16:17]
	v_sub_f32_e32 v16, v28, v27
	v_min_f32_e32 v16, 0, v16
	v_mul_f32_e32 v16, 0x3fb8aa3b, v16
	v_exp_f32_e32 v16, v16
	v_cndmask_b32_e64 v21, 0, v24, s[60:61]
	v_mul_f32_e32 v24, v18, v17
	v_cndmask_b32_e64 v22, 0, v25, s[58:59]
	v_mul_f32_e32 v17, v23, v16
	v_cndmask_b32_e64 v23, 0, v17, s[64:65]
	v_mul_f32_e32 v19, v19, v16
	v_cvt_pk_bf16_f32 v16, v20, v21
	v_cvt_pk_bf16_f32 v17, v22, v23
	ds_write_b128 v144, v[20:23]
	ds_write_b64 v145, v[16:17]
	v_cvt_pk_bf16_f32 v16, v29, s0
	v_cvt_pk_bf16_f32 v17, v30, s0
	v_cndmask_b32_e64 v16, v16, 0, s[56:57]
	v_cndmask_b32_e64 v17, 0, v17, s[54:55]
	v_perm_b32 v18, v17, v16, s25
	v_cvt_pk_bf16_f32 v16, v24, s0
	v_cvt_pk_bf16_f32 v17, v19, s0
	v_cndmask_b32_e64 v16, v16, 0, s[62:63]
	v_cndmask_b32_e64 v17, v17, 0, s[66:67]
	v_perm_b32 v19, v17, v16, s25
	v_lshl_add_u64 v[16:17], v[122:123], 0, v[132:133]
	global_store_dwordx2 v[16:17], v[18:19], off
	ds_read_b128 v[18:21], v198
	ds_read_b128 v[22:25], v107 offset:17408
	ds_read_b128 v[26:29], v107 offset:34816
	s_waitcnt lgkmcnt(1)
	v_mfma_f32_16x16x32_bf16 v[22:25], v[18:21], v[22:25], 0
	s_waitcnt lgkmcnt(0)
	v_mfma_f32_16x16x32_bf16 v[18:21], v[18:21], v[26:29], 0
	ds_read_b128 v[26:29], v198 offset:64
	ds_read_b128 v[122:125], v107 offset:17472
	s_waitcnt lgkmcnt(0)
	v_mfma_f32_16x16x32_bf16 v[22:25], v[26:29], v[122:125], v[22:25]
	ds_read_b128 v[122:125], v107 offset:34880
	s_waitcnt lgkmcnt(0)
	v_mfma_f32_16x16x32_bf16 v[18:21], v[26:29], v[122:125], v[18:21]
	ds_read_b128 v[26:29], v198 offset:128
	ds_read_b128 v[122:125], v107 offset:17536
	s_waitcnt lgkmcnt(0)
	v_mfma_f32_16x16x32_bf16 v[22:25], v[26:29], v[122:125], v[22:25]
	ds_read_b128 v[122:125], v107 offset:34944
	s_waitcnt lgkmcnt(0)
	v_mfma_f32_16x16x32_bf16 v[18:21], v[26:29], v[122:125], v[18:21]
	ds_read_b128 v[26:29], v198 offset:192
	ds_read_b128 v[122:125], v107 offset:17600
	s_waitcnt lgkmcnt(0)
	v_mfma_f32_16x16x32_bf16 v[22:25], v[26:29], v[122:125], v[22:25]
	ds_read_b128 v[122:125], v107 offset:35008
	s_waitcnt lgkmcnt(0)
	v_mfma_f32_16x16x32_bf16 v[18:21], v[26:29], v[122:125], v[18:21]
	ds_read_b128 v[26:29], v146
	ds_read_b32 v30, v109
	s_waitcnt lgkmcnt(0)
	v_sub_f32_e32 v26, v30, v26
	v_min_f32_e32 v26, 0, v26
	v_mul_f32_e32 v26, 0x3fb8aa3b, v26
	v_exp_f32_e32 v26, v26
	s_nop 0
	v_mul_f32_e32 v31, v18, v26
	v_sub_f32_e32 v18, v30, v27
	v_min_f32_e32 v18, 0, v18
	v_mul_f32_e32 v18, 0x3fb8aa3b, v18
	v_exp_f32_e32 v18, v18
	v_mul_f32_e32 v22, v22, v26
	v_mov_b32_e32 v26, v23
	v_mov_b32_e32 v27, v24
	v_mul_f32_e32 v122, v19, v18
	v_sub_f32_e32 v19, v30, v28
	v_min_f32_e32 v19, 0, v19
	v_mul_f32_e32 v19, 0x3fb8aa3b, v19
	v_exp_f32_e32 v19, v19
	v_cndmask_b32_e64 v22, 0, v22, s[68:69]
	v_pk_mul_f32 v[26:27], v[26:27], v[18:19]
	v_sub_f32_e32 v18, v30, v29
	v_min_f32_e32 v18, 0, v18
	v_mul_f32_e32 v18, 0x3fb8aa3b, v18
	v_exp_f32_e32 v18, v18
	v_mul_f32_e32 v20, v20, v19
	v_cndmask_b32_e64 v24, 0, v27, s[72:73]
	v_cndmask_b32_e64 v23, 0, v26, s[74:75]
	v_mul_f32_e32 v19, v25, v18
	v_cndmask_b32_e64 v25, 0, v19, s[78:79]
	v_mul_f32_e32 v21, v21, v18
	v_cvt_pk_bf16_f32 v18, v22, v23
	v_cvt_pk_bf16_f32 v19, v24, v25
	ds_write_b128 v144, v[22:25] offset:64
	ds_write_b64 v145, v[18:19] offset:32
	v_cvt_pk_bf16_f32 v18, v31, s0
	v_cvt_pk_bf16_f32 v19, v122, s0
	v_cndmask_b32_e64 v18, v18, 0, s[70:71]
	v_cndmask_b32_e64 v19, 0, v19, s[68:69]
	v_perm_b32 v18, v19, v18, s25
	v_cvt_pk_bf16_f32 v19, v20, s0
	v_cvt_pk_bf16_f32 v20, v21, s0
	v_cndmask_b32_e64 v19, v19, 0, s[76:77]
	v_cndmask_b32_e64 v20, v20, 0, s[80:81]
	v_perm_b32 v19, v20, v19, s25
	global_store_dwordx2 v[16:17], v[18:19], off offset:32
	s_waitcnt lgkmcnt(0)
	s_barrier
; DI void gdn_prep_item(const P& p, int l, int item, unsigned char* smem) {
;     ...
;     if (tid < 64) {
;         const int I = tid >> 4, cc = tid & 15;
;         float tt[16];
; #pragma unroll
;         for (int r = 0; r < 16; ++r) tt[r] = (r == cc) ? 1.f : 0.f;
; #pragma unroll
;         for (int j = 0; j < 15; ++j) {
;             const float tj = tt[j];
; #pragma unroll
;             for (int r = j + 1; r < 16; ++r) tt[r] -= sL[(16 * I + r) * LS + 16 * I + j] * tj;
;         }
; #pragma unroll
;         for (int r = 0; r < 16; ++r) sTd[(I * 16 + r) * 24 + cc] = f2bf(tt[r]);
;     }
	s_and_saveexec_b64 vcc, s[38:39]
	s_cbranch_execz .LBB0_321
	ds_write_b16 v89, v87
	ds_read_b128 v[228:231], v86 offset:272
	ds_read_b128 v[232:235], v86 offset:544
	ds_read_b128 v[236:239], v86 offset:816
	ds_read_b128 v[240:243], v86 offset:1088
	ds_read_b128 v[244:247], v86 offset:1360
	ds_read_b128 v[248:251], v86 offset:1632
	ds_read_b128 v[202:205], v86 offset:1904
	ds_read_b128 v[206:209], v86 offset:2176
	ds_read_b128 v[210:213], v86 offset:2448
	ds_read_b128 v[122:125], v86 offset:2720
	s_waitcnt lgkmcnt(7)
	v_fma_f32 v16, -v147, v228, v162
	v_fma_f32 v17, -v147, v232, v161
	v_fma_f32 v18, -v147, v236, v160
	v_fma_f32 v17, -v16, v233, v17
	v_fma_f32 v18, -v16, v237, v18
	v_fma_f32 v18, -v17, v238, v18
	ds_read_b128 v[228:231], v86 offset:2992
	ds_read_b128 v[232:235], v86 offset:3264
	ds_read_b128 v[236:239], v86 offset:3536
	s_waitcnt lgkmcnt(8)
	v_fma_f32 v19, -v147, v240, v159
	v_fma_f32 v20, -v147, v244, v158
	v_fma_f32 v19, -v16, v241, v19
	v_fma_f32 v20, -v16, v245, v20
	v_fma_f32 v19, -v17, v242, v19
	v_fma_f32 v20, -v17, v246, v20
	v_fma_f32 v19, -v18, v243, v19
	v_fma_f32 v20, -v18, v247, v20
	ds_read_b128 v[240:243], v86 offset:3808
	ds_read_b128 v[244:247], v86 offset:4080
	s_waitcnt lgkmcnt(8)
	v_fma_f32 v21, -v147, v248, v157
	v_fma_f32 v22, -v147, v202, v156
	v_fma_f32 v21, -v16, v249, v21
	v_fma_f32 v22, -v16, v203, v22
	v_fma_f32 v21, -v17, v250, v21
	v_fma_f32 v22, -v17, v204, v22
	v_fma_f32 v21, -v18, v251, v21
	v_fma_f32 v22, -v18, v205, v22
	ds_read_b128 v[248:251], v86 offset:1376
	ds_read_b128 v[202:205], v86 offset:1648
	s_waitcnt lgkmcnt(8)
	v_fma_f32 v23, -v147, v206, v155
	v_fma_f32 v24, -v147, v210, v154
	v_fma_f32 v23, -v16, v207, v23
	v_fma_f32 v24, -v16, v211, v24
	v_fma_f32 v23, -v17, v208, v23
	v_fma_f32 v24, -v17, v212, v24
	v_fma_f32 v23, -v18, v209, v23
	v_fma_f32 v24, -v18, v213, v24
	ds_read_b128 v[206:209], v86 offset:1920
	ds_read_b128 v[210:213], v86 offset:2192
	s_waitcnt lgkmcnt(8)
	v_fma_f32 v25, -v147, v122, v153
	v_fma_f32 v26, -v147, v228, v152
	v_fma_f32 v25, -v16, v123, v25
	v_fma_f32 v26, -v16, v229, v26
	v_fma_f32 v25, -v17, v124, v25
	v_fma_f32 v26, -v17, v230, v26
	v_fma_f32 v25, -v18, v125, v25
	v_fma_f32 v26, -v18, v231, v26
	ds_read_b128 v[122:125], v86 offset:2464
	ds_read_b128 v[228:231], v86 offset:2736
	s_waitcnt lgkmcnt(8)
	v_fma_f32 v27, -v147, v232, v151
	v_fma_f32 v28, -v147, v236, v150
	v_fma_f32 v27, -v16, v233, v27
	v_fma_f32 v28, -v16, v237, v28
	v_fma_f32 v27, -v17, v234, v27
	v_fma_f32 v28, -v17, v238, v28
	v_fma_f32 v27, -v18, v235, v27
	v_fma_f32 v28, -v18, v239, v28
	ds_read_b128 v[232:235], v86 offset:3008
	ds_read_b128 v[236:239], v86 offset:3280
	s_waitcnt lgkmcnt(8)
	v_fma_f32 v29, -v147, v240, v149
	v_fma_f32 v30, -v147, v244, v148
	v_fma_f32 v29, -v16, v241, v29
	v_fma_f32 v30, -v16, v245, v30
	v_fma_f32 v29, -v17, v242, v29
	v_fma_f32 v30, -v17, v246, v30
	v_fma_f32 v29, -v18, v243, v29
	v_fma_f32 v30, -v18, v247, v30
	ds_read_b128 v[240:243], v86 offset:3552
	ds_read_b128 v[244:247], v86 offset:3824
	s_waitcnt lgkmcnt(7)
	v_fma_f32 v20, -v19, v248, v20
	v_fma_f32 v21, -v19, v202, v21
	v_fma_f32 v22, -v19, v206, v22
	v_fma_f32 v21, -v20, v203, v21
	v_fma_f32 v22, -v20, v207, v22
	v_fma_f32 v22, -v21, v208, v22
	ds_read_b128 v[248:251], v86 offset:4096
	ds_read_b128 v[202:205], v86 offset:2480
	ds_read_b128 v[206:209], v86 offset:2752
	s_waitcnt lgkmcnt(8)
	v_fma_f32 v23, -v19, v210, v23
	v_fma_f32 v24, -v19, v122, v24
	v_fma_f32 v23, -v20, v211, v23
	v_fma_f32 v24, -v20, v123, v24
	v_fma_f32 v23, -v21, v212, v23
	v_fma_f32 v24, -v21, v124, v24
	v_fma_f32 v23, -v22, v213, v23
	v_fma_f32 v24, -v22, v125, v24
	ds_read_b128 v[210:213], v86 offset:3024
	ds_read_b128 v[122:125], v86 offset:3296
	s_waitcnt lgkmcnt(8)
	v_fma_f32 v25, -v19, v228, v25
	v_fma_f32 v26, -v19, v232, v26
	v_fma_f32 v25, -v20, v229, v25
	v_fma_f32 v26, -v20, v233, v26
	v_fma_f32 v25, -v21, v230, v25
	v_fma_f32 v26, -v21, v234, v26
	v_fma_f32 v25, -v22, v231, v25
	v_fma_f32 v26, -v22, v235, v26
	ds_read_b128 v[228:231], v86 offset:3568
	ds_read_b128 v[232:235], v86 offset:3840
	s_waitcnt lgkmcnt(8)
	v_fma_f32 v27, -v19, v236, v27
	v_fma_f32 v28, -v19, v240, v28
	v_fma_f32 v27, -v20, v237, v27
	v_fma_f32 v28, -v20, v241, v28
	v_fma_f32 v27, -v21, v238, v27
	v_fma_f32 v28, -v21, v242, v28
	v_fma_f32 v27, -v22, v239, v27
	v_fma_f32 v28, -v22, v243, v28
	ds_read_b128 v[236:239], v86 offset:4112
	ds_read_b128 v[240:243], v86 offset:3584
	s_waitcnt lgkmcnt(8)
	v_fma_f32 v29, -v19, v244, v29
	v_fma_f32 v30, -v19, v248, v30
	v_fma_f32 v29, -v20, v245, v29
	v_fma_f32 v30, -v20, v249, v30
	v_fma_f32 v29, -v21, v246, v29
	v_fma_f32 v30, -v21, v250, v30
	v_fma_f32 v29, -v22, v247, v29
	v_fma_f32 v30, -v22, v251, v30
	ds_read_b128 v[244:247], v86 offset:3856
	ds_read_b128 v[248:251], v86 offset:4128
	s_waitcnt lgkmcnt(7)
	v_fma_f32 v24, -v23, v202, v24
	v_fma_f32 v25, -v23, v206, v25
	v_fma_f32 v26, -v23, v210, v26
	v_fma_f32 v25, -v24, v207, v25
	v_fma_f32 v26, -v24, v211, v26
	v_fma_f32 v26, -v25, v212, v26
	s_waitcnt lgkmcnt(5)
	v_fma_f32 v27, -v23, v122, v27
	v_fma_f32 v28, -v23, v228, v28
	v_fma_f32 v27, -v24, v123, v27
	v_fma_f32 v28, -v24, v229, v28
	v_fma_f32 v27, -v25, v124, v27
	v_fma_f32 v28, -v25, v230, v28
	v_fma_f32 v27, -v26, v125, v27
	v_fma_f32 v28, -v26, v231, v28
	s_waitcnt lgkmcnt(3)
	v_fma_f32 v29, -v23, v232, v29
	v_fma_f32 v30, -v23, v236, v30
	v_fma_f32 v29, -v24, v233, v29
	v_fma_f32 v30, -v24, v237, v30
	v_fma_f32 v29, -v25, v234, v29
	v_fma_f32 v30, -v25, v238, v30
	v_fma_f32 v29, -v26, v235, v29
	v_fma_f32 v30, -v26, v239, v30
	s_waitcnt lgkmcnt(0)
	v_fma_f32 v28, -v27, v240, v28
	v_fma_f32 v29, -v27, v244, v29
	v_fma_f32 v30, -v27, v248, v30
	v_fma_f32 v29, -v28, v245, v29
	v_fma_f32 v30, -v28, v249, v30
	v_fma_f32 v30, -v29, v250, v30
	v_cvt_pk_bf16_f32 v31, v16, s0
	ds_write_b16 v89, v31 offset:48
	v_cvt_pk_bf16_f32 v31, v17, s0
	ds_write_b16 v89, v31 offset:96
	v_cvt_pk_bf16_f32 v31, v18, s0
	ds_write_b16 v89, v31 offset:144
	v_cvt_pk_bf16_f32 v31, v19, s0
	ds_write_b16 v89, v31 offset:192
	v_cvt_pk_bf16_f32 v31, v20, s0
	ds_write_b16 v89, v31 offset:240
	v_cvt_pk_bf16_f32 v31, v21, s0
	ds_write_b16 v89, v31 offset:288
	v_cvt_pk_bf16_f32 v31, v22, s0
	ds_write_b16 v89, v31 offset:336
	v_cvt_pk_bf16_f32 v31, v23, s0
	ds_write_b16 v89, v31 offset:384
	v_cvt_pk_bf16_f32 v31, v24, s0
	ds_write_b16 v89, v31 offset:432
	v_cvt_pk_bf16_f32 v31, v25, s0
	ds_write_b16 v89, v31 offset:480
	v_cvt_pk_bf16_f32 v31, v26, s0
	ds_write_b16 v89, v31 offset:528
	v_cvt_pk_bf16_f32 v31, v27, s0
	ds_write_b16 v89, v31 offset:576
	v_cvt_pk_bf16_f32 v31, v28, s0
	ds_write_b16 v89, v31 offset:624
	v_cvt_pk_bf16_f32 v31, v29, s0
	ds_write_b16 v89, v31 offset:672
	v_cvt_pk_bf16_f32 v31, v30, s0
	ds_write_b16 v163, v31
	s_branch .LBB0_321
